# GEMM tile epilogues no longer aligned between the two wave groups (per-tile alignment barriers removed, one closing barrier for waves 0-3)
# speedup vs baseline: 1.0400x; 1.0050x over previous
; #define PG8_STAGE(bufoff, gbase, voff) do { _Pragma("unroll") for (int _i = 0; _i < 2; ++_i) \
;         glds16((const void*)(gbase), (voff)[_i], (unsigned)__builtin_amdgcn_readfirstlane(lds0 + (bufoff) + ldsw + _i * 8192)); } while (0)
; #define PG8_LDA(dst, b, h) do { _Pragma("unroll") for (int m = 0; m < 4; ++m) _Pragma("unroll") for (int k = 0; k < 2; ++k) dst[m][k] = *(const LAS bf16x8*)(lds + PG8_SA(b, h) + aoff + m * 2048 + k * 1024); } while (0)
; #define PG8_LDB(dst, b, h) do { _Pragma("unroll") for (int n = 0; n < 2; ++n) _Pragma("unroll") for (int k = 0; k < 2; ++k) dst[n][k] = *(const LAS bf16x8*)(lds + PG8_SB(b, h) + boff + n * 2048 + k * 1024); } while (0)
; #define PG8_MMA(ai, bj, At, Bt) do { __builtin_amdgcn_s_setprio(1); _Pragma("unroll") for (int m = 0; m < 4; ++m) _Pragma("unroll") for (int n = 0; n < 2; ++n) _Pragma("unroll") for (int k = 0; k < 2; ++k) \
;         acc[ai][bj][m][n] = __builtin_amdgcn_mfma_f32_16x16x32_bf16(Bt[n][k], At[m][k], acc[ai][bj][m][n], 0, 0, 0); __builtin_amdgcn_s_setprio(0); } while (0)
; #define PG8_WAIT_V(n) asm volatile("s_waitcnt vmcnt(" #n ")" ::: "memory")
; #define PG8_WAIT_L(n) asm volatile("s_waitcnt lgkmcnt(" #n ")" ::: "memory")
; #define PG8_BAR __builtin_amdgcn_s_barrier()
; #define PG8_SCHED __builtin_amdgcn_sched_barrier(0)
; template <class Epi, class Sched, bool ALIGN_EPI = false, bool SP2 = false>
; __device__ __forceinline__ void gemm_phase(LAS unsigned char* lds, const Gemm g, const Sched& S, const Epi& E) {
;     ...
;             const char* a2 = last ? nA : cA + (size_t)(t + 2) * kstep; const char* b2 = last ? nB : cB + (size_t)(t + 2) * kstep;
;     ...
;             PG8_LDB(B0, 0, 0); PG8_LDB(B1, 0, 1); PG8_SCHED; PG8_LDA(At, 0, 0); PG8_STAGE(PG8_SA(1, 1), a1 + hstep, voffA);
;             PG8_WAIT_V(8); PG8_WAIT_L(0); PG8_BAR; PG8_MMA(0, 0, At, B0); PG8_MMA(0, 1, At, B1); PG8_BAR; PG8_SCHED;
;             PG8_LDA(At, 0, 1); PG8_STAGE(PG8_SB(0, 0), b2, voffB); PG8_STAGE(PG8_SB(0, 1), b2 + hstep, voffB); PG8_STAGE(PG8_SA(0, 0), a2, voffA);
;             PG8_WAIT_V(8); PG8_WAIT_L(0); PG8_BAR; PG8_MMA(1, 0, At, B0); PG8_MMA(1, 1, At, B1); PG8_BAR; PG8_SCHED;
.LBB0_117:
	ds_read_b128 v[132:135], v153
	ds_read_b128 v[136:139], v153 offset:1024
	ds_read_b128 v[142:145], v153 offset:2048
	ds_read_b128 v[168:171], v153 offset:3072
	ds_read_b128 v[172:175], v154
	ds_read_b128 v[176:179], v154 offset:1024
	ds_read_b128 v[180:183], v154 offset:2048
	ds_read_b128 v[184:187], v154 offset:3072
	s_add_u32 vcc_lo, s22, 0x100
	s_addc_u32 vcc_hi, s23, 0
	s_cmp_eq_u32 s77, 12
	s_cselect_b32 s10, s73, vcc_lo
	s_cselect_b32 s11, s29, vcc_hi
	s_cselect_b32 s46, s74, s75
	s_cselect_b32 s47, s13, s76
	s_add_u32 s82, s10, 0x80
	s_addc_u32 s83, s11, 0
	ds_read_b128 v[188:191], v155
	ds_read_b128 v[192:195], v155 offset:1024
	ds_read_b128 v[196:199], v155 offset:2048
	ds_read_b128 v[200:203], v155 offset:3072
	ds_read_b128 v[204:207], v155 offset:4096
	ds_read_b128 v[208:211], v155 offset:5120
	ds_read_b128 v[212:215], v155 offset:6144
	ds_read_b128 v[216:219], v155 offset:7168
	s_add_u32 s22, s22, 0x40080
	s_addc_u32 s23, s23, 0
	s_mov_b32 s26, m0
	s_mov_b32 m0, s71
	s_nop 0
	global_load_lds_dwordx4 v0, s[22:23]
	s_mov_b32 m0, s26
	s_add_i32 s26, s2, 0xe000
	s_mov_b32 s36, m0
	s_mov_b32 m0, s26
	s_nop 0
	global_load_lds_dwordx4 v149, s[22:23]
	s_mov_b32 m0, s36
	s_waitcnt vmcnt(8)
	s_waitcnt lgkmcnt(0)
	s_barrier
	s_setprio 1
	s_waitcnt lgkmcnt(7)
	v_mfma_f32_16x16x32_bf16 v[126:129], v[132:135], v[188:191], v[126:129]
	v_mfma_f32_16x16x32_bf16 v[122:125], v[142:145], v[188:191], v[122:125]
	s_waitcnt lgkmcnt(5)
	v_mfma_f32_16x16x32_bf16 v[118:121], v[132:135], v[196:199], v[118:121]
	v_mfma_f32_16x16x32_bf16 v[110:113], v[142:145], v[196:199], v[110:113]
	s_waitcnt lgkmcnt(3)
	v_mfma_f32_16x16x32_bf16 v[102:105], v[132:135], v[204:207], v[102:105]
	v_mfma_f32_16x16x32_bf16 v[94:97], v[142:145], v[204:207], v[94:97]
	s_waitcnt lgkmcnt(1)
	v_mfma_f32_16x16x32_bf16 v[86:89], v[132:135], v[212:215], v[86:89]
	v_mfma_f32_16x16x32_bf16 v[78:81], v[142:145], v[212:215], v[78:81]
	v_mfma_f32_16x16x32_bf16 v[126:129], v[136:139], v[192:195], v[126:129]
	v_mfma_f32_16x16x32_bf16 v[122:125], v[168:171], v[192:195], v[122:125]
	v_mfma_f32_16x16x32_bf16 v[118:121], v[136:139], v[200:203], v[118:121]
	v_mfma_f32_16x16x32_bf16 v[110:113], v[168:171], v[200:203], v[110:113]
	v_mfma_f32_16x16x32_bf16 v[102:105], v[136:139], v[208:211], v[102:105]
	v_mfma_f32_16x16x32_bf16 v[94:97], v[168:171], v[208:211], v[94:97]
	s_waitcnt lgkmcnt(0)
	v_mfma_f32_16x16x32_bf16 v[86:89], v[136:139], v[216:219], v[86:89]
	v_mfma_f32_16x16x32_bf16 v[78:81], v[168:171], v[216:219], v[78:81]
	s_setprio 0
	s_setprio 1
	v_mfma_f32_16x16x32_bf16 v[114:117], v[172:175], v[188:191], v[114:117]
	v_mfma_f32_16x16x32_bf16 v[106:109], v[180:183], v[188:191], v[106:109]
	v_mfma_f32_16x16x32_bf16 v[98:101], v[172:175], v[196:199], v[98:101]
	v_mfma_f32_16x16x32_bf16 v[90:93], v[180:183], v[196:199], v[90:93]
	v_mfma_f32_16x16x32_bf16 v[82:85], v[172:175], v[204:207], v[82:85]
	v_mfma_f32_16x16x32_bf16 v[74:77], v[180:183], v[204:207], v[74:77]
	v_mfma_f32_16x16x32_bf16 v[70:73], v[172:175], v[212:215], v[70:73]
	v_mfma_f32_16x16x32_bf16 v[66:69], v[180:183], v[212:215], v[66:69]
	v_mfma_f32_16x16x32_bf16 v[114:117], v[176:179], v[192:195], v[114:117]
	v_mfma_f32_16x16x32_bf16 v[106:109], v[184:187], v[192:195], v[106:109]
	v_mfma_f32_16x16x32_bf16 v[98:101], v[176:179], v[200:203], v[98:101]
	v_mfma_f32_16x16x32_bf16 v[90:93], v[184:187], v[200:203], v[90:93]
	v_mfma_f32_16x16x32_bf16 v[82:85], v[176:179], v[208:211], v[82:85]
	v_mfma_f32_16x16x32_bf16 v[74:77], v[184:187], v[208:211], v[74:77]
	v_mfma_f32_16x16x32_bf16 v[70:73], v[176:179], v[216:219], v[70:73]
	v_mfma_f32_16x16x32_bf16 v[66:69], v[184:187], v[216:219], v[66:69]
	s_setprio 0
	s_barrier
	ds_read_b128 v[188:191], v155 offset:16384
	ds_read_b128 v[192:195], v155 offset:17408
	ds_read_b128 v[196:199], v155 offset:18432
	ds_read_b128 v[200:203], v155 offset:19456
	ds_read_b128 v[204:207], v155 offset:20480
	ds_read_b128 v[208:211], v155 offset:21504
	ds_read_b128 v[212:215], v155 offset:22528
	ds_read_b128 v[216:219], v155 offset:23552
	s_mov_b32 s22, m0
	s_mov_b32 m0, s21
	s_nop 0
	global_load_lds_dwordx4 v148, s[46:47]
	s_mov_b32 m0, s22
	s_nop 0
	s_mov_b32 s22, m0
	s_mov_b32 m0, s56
	s_nop 0
	global_load_lds_dwordx4 v150, s[46:47]
	s_mov_b32 m0, s22
	s_add_u32 s22, s46, 0x40000
	s_addc_u32 s23, s47, 0
	s_mov_b32 s26, m0
	s_mov_b32 m0, s57
	s_nop 0
	global_load_lds_dwordx4 v148, s[22:23]
	s_mov_b32 m0, s26
	s_nop 0
	s_mov_b32 s26, m0
	s_mov_b32 m0, s58
	s_nop 0
	global_load_lds_dwordx4 v150, s[22:23]
	s_mov_b32 m0, s26
	s_mov_b32 s22, m0
	s_mov_b32 m0, s2
	s_nop 0
	global_load_lds_dwordx4 v0, s[10:11]
	s_mov_b32 m0, s22
	s_nop 0
	s_mov_b32 s22, m0
	s_mov_b32 m0, s59
	s_nop 0
	global_load_lds_dwordx4 v149, s[10:11]
	s_mov_b32 m0, s22
	s_waitcnt vmcnt(8)
	s_waitcnt lgkmcnt(0)
	s_barrier
; #define PG8_STAGE(bufoff, gbase, voff) do { _Pragma("unroll") for (int _i = 0; _i < 2; ++_i) \
;         glds16((const void*)(gbase), (voff)[_i], (unsigned)__builtin_amdgcn_readfirstlane(lds0 + (bufoff) + ldsw + _i * 8192)); } while (0)
; #define PG8_LDA(dst, b, h) do { _Pragma("unroll") for (int m = 0; m < 4; ++m) _Pragma("unroll") for (int k = 0; k < 2; ++k) dst[m][k] = *(const LAS bf16x8*)(lds + PG8_SA(b, h) + aoff + m * 2048 + k * 1024); } while (0)
; #define PG8_LDB(dst, b, h) do { _Pragma("unroll") for (int n = 0; n < 2; ++n) _Pragma("unroll") for (int k = 0; k < 2; ++k) dst[n][k] = *(const LAS bf16x8*)(lds + PG8_SB(b, h) + boff + n * 2048 + k * 1024); } while (0)
; #define PG8_MMA(ai, bj, At, Bt) do { __builtin_amdgcn_s_setprio(1); _Pragma("unroll") for (int m = 0; m < 4; ++m) _Pragma("unroll") for (int n = 0; n < 2; ++n) _Pragma("unroll") for (int k = 0; k < 2; ++k) \
;         acc[ai][bj][m][n] = __builtin_amdgcn_mfma_f32_16x16x32_bf16(Bt[n][k], At[m][k], acc[ai][bj][m][n], 0, 0, 0); __builtin_amdgcn_s_setprio(0); } while (0)
; #define PG8_WAIT_V(n) asm volatile("s_waitcnt vmcnt(" #n ")" ::: "memory")
; #define PG8_WAIT_L(n) asm volatile("s_waitcnt lgkmcnt(" #n ")" ::: "memory")
; #define PG8_BAR __builtin_amdgcn_s_barrier()
; #define PG8_SCHED __builtin_amdgcn_sched_barrier(0)
; template <class Epi, class Sched, bool ALIGN_EPI = false, bool SP2 = false>
; __device__ __forceinline__ void gemm_phase(LAS unsigned char* lds, const Gemm g, const Sched& S, const Epi& E) {
;     ...
;             PG8_WAIT_V(8); PG8_WAIT_L(0); PG8_BAR; PG8_MMA(1, 0, At, B0); PG8_MMA(1, 1, At, B1); PG8_BAR; PG8_SCHED;
;             PG8_LDB(B0, 1, 0); PG8_LDB(B1, 1, 1); PG8_SCHED; PG8_LDA(At, 1, 0); PG8_STAGE(PG8_SA(0, 1), a2 + hstep, voffA);
;             PG8_WAIT_V(8); PG8_WAIT_L(0); PG8_BAR; PG8_MMA(0, 0, At, B0); PG8_MMA(0, 1, At, B1); PG8_BAR; PG8_SCHED;
	s_setprio 1
	s_waitcnt lgkmcnt(7)
	v_mfma_f32_16x16x32_bf16 v[62:65], v[132:135], v[188:191], v[62:65]
	v_mfma_f32_16x16x32_bf16 v[58:61], v[142:145], v[188:191], v[58:61]
	s_waitcnt lgkmcnt(5)
	v_mfma_f32_16x16x32_bf16 v[54:57], v[132:135], v[196:199], v[54:57]
	v_mfma_f32_16x16x32_bf16 v[46:49], v[142:145], v[196:199], v[46:49]
	s_waitcnt lgkmcnt(3)
	v_mfma_f32_16x16x32_bf16 v[38:41], v[132:135], v[204:207], v[38:41]
	v_mfma_f32_16x16x32_bf16 v[30:33], v[142:145], v[204:207], v[30:33]
	s_waitcnt lgkmcnt(1)
	v_mfma_f32_16x16x32_bf16 v[22:25], v[132:135], v[212:215], v[22:25]
	v_mfma_f32_16x16x32_bf16 v[14:17], v[142:145], v[212:215], v[14:17]
	v_mfma_f32_16x16x32_bf16 v[62:65], v[136:139], v[192:195], v[62:65]
	v_mfma_f32_16x16x32_bf16 v[58:61], v[168:171], v[192:195], v[58:61]
	v_mfma_f32_16x16x32_bf16 v[54:57], v[136:139], v[200:203], v[54:57]
	v_mfma_f32_16x16x32_bf16 v[46:49], v[168:171], v[200:203], v[46:49]
	v_mfma_f32_16x16x32_bf16 v[38:41], v[136:139], v[208:211], v[38:41]
	v_mfma_f32_16x16x32_bf16 v[30:33], v[168:171], v[208:211], v[30:33]
	s_waitcnt lgkmcnt(0)
	v_mfma_f32_16x16x32_bf16 v[22:25], v[136:139], v[216:219], v[22:25]
	v_mfma_f32_16x16x32_bf16 v[14:17], v[168:171], v[216:219], v[14:17]
	s_setprio 0
	s_setprio 1
	v_mfma_f32_16x16x32_bf16 v[50:53], v[172:175], v[188:191], v[50:53]
	v_mfma_f32_16x16x32_bf16 v[42:45], v[180:183], v[188:191], v[42:45]
	v_mfma_f32_16x16x32_bf16 v[34:37], v[172:175], v[196:199], v[34:37]
	v_mfma_f32_16x16x32_bf16 v[26:29], v[180:183], v[196:199], v[26:29]
	v_mfma_f32_16x16x32_bf16 v[18:21], v[172:175], v[204:207], v[18:21]
	v_mfma_f32_16x16x32_bf16 v[10:13], v[180:183], v[204:207], v[10:13]
	v_mfma_f32_16x16x32_bf16 v[6:9], v[172:175], v[212:215], v[6:9]
	v_mfma_f32_16x16x32_bf16 v[2:5], v[180:183], v[212:215], v[2:5]
	v_mfma_f32_16x16x32_bf16 v[50:53], v[176:179], v[192:195], v[50:53]
	v_mfma_f32_16x16x32_bf16 v[42:45], v[184:187], v[192:195], v[42:45]
	v_mfma_f32_16x16x32_bf16 v[34:37], v[176:179], v[200:203], v[34:37]
	v_mfma_f32_16x16x32_bf16 v[26:29], v[184:187], v[200:203], v[26:29]
	v_mfma_f32_16x16x32_bf16 v[18:21], v[176:179], v[208:211], v[18:21]
	v_mfma_f32_16x16x32_bf16 v[10:13], v[184:187], v[208:211], v[10:13]
	v_mfma_f32_16x16x32_bf16 v[6:9], v[176:179], v[216:219], v[6:9]
	v_mfma_f32_16x16x32_bf16 v[2:5], v[184:187], v[216:219], v[2:5]
	s_setprio 0
	s_barrier
	ds_read_b128 v[132:135], v156
	ds_read_b128 v[136:139], v156 offset:1024
	ds_read_b128 v[142:145], v156 offset:2048
	ds_read_b128 v[168:171], v156 offset:3072
	ds_read_b128 v[172:175], v157
	ds_read_b128 v[176:179], v157 offset:1024
	ds_read_b128 v[180:183], v157 offset:2048
	ds_read_b128 v[184:187], v157 offset:3072
	ds_read_b128 v[188:191], v155 offset:32768
	ds_read_b128 v[192:195], v155 offset:33792
	ds_read_b128 v[196:199], v155 offset:34816
	ds_read_b128 v[200:203], v155 offset:35840
	ds_read_b128 v[204:207], v155 offset:36864
	ds_read_b128 v[208:211], v155 offset:37888
	ds_read_b128 v[212:215], v155 offset:38912
	ds_read_b128 v[216:219], v155 offset:39936
	s_add_u32 s10, s10, 0x40000
	s_addc_u32 s11, s11, 0
	s_mov_b32 s22, m0
	s_mov_b32 m0, s60
	s_nop 0
	global_load_lds_dwordx4 v0, s[10:11]
	s_mov_b32 m0, s22
	s_nop 0
	s_mov_b32 s22, m0
	s_mov_b32 m0, s61
	s_nop 0
	global_load_lds_dwordx4 v149, s[10:11]
	s_mov_b32 m0, s22
	s_waitcnt vmcnt(8)
	s_waitcnt lgkmcnt(0)
	s_barrier
	s_setprio 1
	s_waitcnt lgkmcnt(7)
	v_mfma_f32_16x16x32_bf16 v[126:129], v[132:135], v[188:191], v[126:129]
	v_mfma_f32_16x16x32_bf16 v[122:125], v[142:145], v[188:191], v[122:125]
	s_waitcnt lgkmcnt(5)
	v_mfma_f32_16x16x32_bf16 v[118:121], v[132:135], v[196:199], v[118:121]
	v_mfma_f32_16x16x32_bf16 v[110:113], v[142:145], v[196:199], v[110:113]
	s_waitcnt lgkmcnt(3)
	v_mfma_f32_16x16x32_bf16 v[102:105], v[132:135], v[204:207], v[102:105]
	v_mfma_f32_16x16x32_bf16 v[94:97], v[142:145], v[204:207], v[94:97]
	s_waitcnt lgkmcnt(1)
	v_mfma_f32_16x16x32_bf16 v[86:89], v[132:135], v[212:215], v[86:89]
	v_mfma_f32_16x16x32_bf16 v[78:81], v[142:145], v[212:215], v[78:81]
	v_mfma_f32_16x16x32_bf16 v[126:129], v[136:139], v[192:195], v[126:129]
	v_mfma_f32_16x16x32_bf16 v[122:125], v[168:171], v[192:195], v[122:125]
	v_mfma_f32_16x16x32_bf16 v[118:121], v[136:139], v[200:203], v[118:121]
	v_mfma_f32_16x16x32_bf16 v[110:113], v[168:171], v[200:203], v[110:113]
	v_mfma_f32_16x16x32_bf16 v[102:105], v[136:139], v[208:211], v[102:105]
	v_mfma_f32_16x16x32_bf16 v[94:97], v[168:171], v[208:211], v[94:97]
	s_waitcnt lgkmcnt(0)
	v_mfma_f32_16x16x32_bf16 v[86:89], v[136:139], v[216:219], v[86:89]
	v_mfma_f32_16x16x32_bf16 v[78:81], v[168:171], v[216:219], v[78:81]
	s_setprio 0
	s_setprio 1
	v_mfma_f32_16x16x32_bf16 v[114:117], v[172:175], v[188:191], v[114:117]
	v_mfma_f32_16x16x32_bf16 v[106:109], v[180:183], v[188:191], v[106:109]
	v_mfma_f32_16x16x32_bf16 v[98:101], v[172:175], v[196:199], v[98:101]
	v_mfma_f32_16x16x32_bf16 v[90:93], v[180:183], v[196:199], v[90:93]
	v_mfma_f32_16x16x32_bf16 v[82:85], v[172:175], v[204:207], v[82:85]
	v_mfma_f32_16x16x32_bf16 v[74:77], v[180:183], v[204:207], v[74:77]
	v_mfma_f32_16x16x32_bf16 v[70:73], v[172:175], v[212:215], v[70:73]
	v_mfma_f32_16x16x32_bf16 v[66:69], v[180:183], v[212:215], v[66:69]
	v_mfma_f32_16x16x32_bf16 v[114:117], v[176:179], v[192:195], v[114:117]
	v_mfma_f32_16x16x32_bf16 v[106:109], v[184:187], v[192:195], v[106:109]
	v_mfma_f32_16x16x32_bf16 v[98:101], v[176:179], v[200:203], v[98:101]
	v_mfma_f32_16x16x32_bf16 v[90:93], v[184:187], v[200:203], v[90:93]
	v_mfma_f32_16x16x32_bf16 v[82:85], v[176:179], v[208:211], v[82:85]
	v_mfma_f32_16x16x32_bf16 v[74:77], v[184:187], v[208:211], v[74:77]
	v_mfma_f32_16x16x32_bf16 v[70:73], v[176:179], v[216:219], v[70:73]
	v_mfma_f32_16x16x32_bf16 v[66:69], v[184:187], v[216:219], v[66:69]
	s_setprio 0
	s_barrier
; #define PG8_STAGE(bufoff, gbase, voff) do { _Pragma("unroll") for (int _i = 0; _i < 2; ++_i) \
;         glds16((const void*)(gbase), (voff)[_i], (unsigned)__builtin_amdgcn_readfirstlane(lds0 + (bufoff) + ldsw + _i * 8192)); } while (0)
; #define PG8_LDA(dst, b, h) do { _Pragma("unroll") for (int m = 0; m < 4; ++m) _Pragma("unroll") for (int k = 0; k < 2; ++k) dst[m][k] = *(const LAS bf16x8*)(lds + PG8_SA(b, h) + aoff + m * 2048 + k * 1024); } while (0)
; #define PG8_WAIT_V(n) asm volatile("s_waitcnt vmcnt(" #n ")" ::: "memory")
; #define PG8_WAIT_L(n) asm volatile("s_waitcnt lgkmcnt(" #n ")" ::: "memory")
;     __device__ __forceinline__ void operator()(const f32x4 (&acc)[2][2][4][2], const Unit& u, int wr, int wc, int fr, int fq) const {
;     ...
;         if (kb != nullptr && u.pn >= 4 && u.pn < 8) {
;             float mx0 = 0.f, mx1 = 0.f;
; #pragma unroll
;             for (int ai = 0; ai < 2; ++ai)
; #pragma unroll
;                 for (int m = 0; m < 4; ++m) {
;                     const f32x4 a0 = acc[ai][0][m][0], a1 = acc[ai][0][m][1], b0 = acc[ai][1][m][0], b1 = acc[ai][1][m][1];
;                     float s0 = (a0[0] * a0[0] + a0[1] * a0[1]) + (a0[2] * a0[2] + a0[3] * a0[3]) + (a1[0] * a1[0] + a1[1] * a1[1]) + (a1[2] * a1[2] + a1[3] * a1[3]);
;                     float s1 = (b0[0] * b0[0] + b0[1] * b0[1]) + (b0[2] * b0[2] + b0[3] * b0[3]) + (b1[0] * b1[0] + b1[1] * b1[1]) + (b1[2] * b1[2] + b1[3] * b1[3]);
;                     s0 += __shfl_xor(s0, 16); s0 += __shfl_xor(s0, 32); s1 += __shfl_xor(s1, 16); s1 += __shfl_xor(s1, 32);
;                     mx0 = __builtin_fmaxf(mx0, s0); mx1 = __builtin_fmaxf(mx1, s1);
;                 }
; #pragma unroll
;             for (int o = 1; o < 16; o <<= 1) { mx0 = __builtin_fmaxf(mx0, __shfl_xor(mx0, o)); mx1 = __builtin_fmaxf(mx1, __shfl_xor(mx1, o)); }
; template <class Epi, class Sched, bool ALIGN_EPI = false, bool SP2 = false>
; __device__ __forceinline__ void gemm_phase(LAS unsigned char* lds, const Gemm g, const Sched& S, const Epi& E) {
;     ...
;             PG8_LDA(At, 1, 1); PG8_STAGE(PG8_SB(1, 0), b3, voffB); PG8_STAGE(PG8_SB(1, 1), b3 + hstep, voffB); PG8_STAGE(PG8_SA(1, 0), a3, voffA);
;             PG8_WAIT_V(8); PG8_WAIT_L(0); PG8_BAR; PG8_MMA(1, 0, At, B0); PG8_MMA(1, 1, At, B1); PG8_BAR; PG8_SCHED;
;     ...
;         if constexpr (ALIGN_EPI) { if (wr == 0) PG8_BAR; }
	ds_read_b128 v[188:191], v155 offset:49152
	ds_read_b128 v[192:195], v155 offset:50176
	ds_read_b128 v[196:199], v155 offset:51200
	ds_read_b128 v[200:203], v155 offset:52224
	ds_read_b128 v[204:207], v155 offset:53248
	ds_read_b128 v[208:211], v155 offset:54272
	ds_read_b128 v[212:215], v155 offset:55296
	ds_read_b128 v[216:219], v155 offset:56320
	s_add_u32 s10, s46, 0x80
	s_addc_u32 s11, s47, 0
	s_mov_b32 s22, m0
	s_mov_b32 m0, s65
	s_nop 0
	global_load_lds_dwordx4 v148, s[10:11]
	s_mov_b32 m0, s22
	s_nop 0
	s_mov_b32 s22, m0
	s_mov_b32 m0, s66
	s_nop 0
	global_load_lds_dwordx4 v150, s[10:11]
	s_mov_b32 m0, s22
	s_add_u32 s10, s46, 0x40080
	s_addc_u32 s11, s47, 0
	s_mov_b32 s22, m0
	s_mov_b32 m0, s69
	s_nop 0
	global_load_lds_dwordx4 v148, s[10:11]
	s_mov_b32 m0, s22
	s_nop 0
	s_mov_b32 s22, m0
	s_mov_b32 m0, s70
	s_nop 0
	global_load_lds_dwordx4 v150, s[10:11]
	s_mov_b32 m0, s22
	s_mov_b32 s10, m0
	s_mov_b32 m0, s67
	s_nop 0
	global_load_lds_dwordx4 v0, s[82:83]
	s_mov_b32 m0, s10
	s_nop 0
	s_mov_b32 s10, m0
	s_mov_b32 m0, s68
	s_nop 0
	global_load_lds_dwordx4 v149, s[82:83]
	s_mov_b32 m0, s10
	s_waitcnt vmcnt(8)
	s_waitcnt lgkmcnt(0)
	s_barrier
	s_setprio 1
	s_waitcnt lgkmcnt(7)
	v_mfma_f32_16x16x32_bf16 v[62:65], v[132:135], v[188:191], v[62:65]
	v_mfma_f32_16x16x32_bf16 v[58:61], v[142:145], v[188:191], v[58:61]
	s_waitcnt lgkmcnt(5)
	v_mfma_f32_16x16x32_bf16 v[54:57], v[132:135], v[196:199], v[54:57]
	v_mfma_f32_16x16x32_bf16 v[46:49], v[142:145], v[196:199], v[46:49]
	s_waitcnt lgkmcnt(3)
	v_mfma_f32_16x16x32_bf16 v[38:41], v[132:135], v[204:207], v[38:41]
	v_mfma_f32_16x16x32_bf16 v[30:33], v[142:145], v[204:207], v[30:33]
	s_waitcnt lgkmcnt(1)
	v_mfma_f32_16x16x32_bf16 v[22:25], v[132:135], v[212:215], v[22:25]
	v_mfma_f32_16x16x32_bf16 v[14:17], v[142:145], v[212:215], v[14:17]
	v_mfma_f32_16x16x32_bf16 v[62:65], v[136:139], v[192:195], v[62:65]
	v_mfma_f32_16x16x32_bf16 v[58:61], v[168:171], v[192:195], v[58:61]
	v_mfma_f32_16x16x32_bf16 v[54:57], v[136:139], v[200:203], v[54:57]
	v_mfma_f32_16x16x32_bf16 v[46:49], v[168:171], v[200:203], v[46:49]
	v_mfma_f32_16x16x32_bf16 v[38:41], v[136:139], v[208:211], v[38:41]
	v_mfma_f32_16x16x32_bf16 v[30:33], v[168:171], v[208:211], v[30:33]
	s_waitcnt lgkmcnt(0)
	v_mfma_f32_16x16x32_bf16 v[22:25], v[136:139], v[216:219], v[22:25]
	v_mfma_f32_16x16x32_bf16 v[14:17], v[168:171], v[216:219], v[14:17]
	s_setprio 0
	s_setprio 1
	v_mfma_f32_16x16x32_bf16 v[50:53], v[172:175], v[188:191], v[50:53]
	v_mfma_f32_16x16x32_bf16 v[42:45], v[180:183], v[188:191], v[42:45]
	v_mfma_f32_16x16x32_bf16 v[34:37], v[172:175], v[196:199], v[34:37]
	v_mfma_f32_16x16x32_bf16 v[26:29], v[180:183], v[196:199], v[26:29]
	v_mfma_f32_16x16x32_bf16 v[18:21], v[172:175], v[204:207], v[18:21]
	v_mfma_f32_16x16x32_bf16 v[10:13], v[180:183], v[204:207], v[10:13]
	v_mfma_f32_16x16x32_bf16 v[6:9], v[172:175], v[212:215], v[6:9]
	v_mfma_f32_16x16x32_bf16 v[2:5], v[180:183], v[212:215], v[2:5]
	v_mfma_f32_16x16x32_bf16 v[50:53], v[176:179], v[192:195], v[50:53]
	v_mfma_f32_16x16x32_bf16 v[42:45], v[184:187], v[192:195], v[42:45]
	v_mfma_f32_16x16x32_bf16 v[34:37], v[176:179], v[200:203], v[34:37]
	v_mfma_f32_16x16x32_bf16 v[26:29], v[184:187], v[200:203], v[26:29]
	v_mfma_f32_16x16x32_bf16 v[18:21], v[176:179], v[208:211], v[18:21]
	v_mfma_f32_16x16x32_bf16 v[10:13], v[184:187], v[208:211], v[10:13]
	v_mfma_f32_16x16x32_bf16 v[6:9], v[176:179], v[216:219], v[6:9]
	v_mfma_f32_16x16x32_bf16 v[2:5], v[184:187], v[216:219], v[2:5]
	s_setprio 0
	s_barrier
	s_add_i32 s77, s77, 2
	s_add_u32 s75, s75, 0x100
	s_addc_u32 s76, s76, 0
	s_cmp_gt_u32 s77, 13
	s_mov_b64 s[22:23], vcc
	s_cbranch_scc0 .LBB0_117
	s_and_b64 vcc, exec, s[90:91]
	s_cbranch_vccz .LBB0_120
.LBB0_120:
	s_and_b32 s10, s94, -4
	s_cmp_eq_u32 s10, 4
	s_cselect_b64 s[10:11], -1, 0
	s_and_b64 s[10:11], s[44:45], s[10:11]
	s_andn2_b64 vcc, exec, s[10:11]
	s_cbranch_vccnz .LBB0_131
	v_mul_f32_e32 v135, v127, v127
	v_mul_f32_e32 v136, v129, v129
	v_fmac_f32_e32 v135, v126, v126
	v_fmac_f32_e32 v136, v128, v128
	v_add_f32_e32 v135, v135, v136
	v_mul_f32_e32 v136, v123, v123
	v_fmac_f32_e32 v136, v122, v122
	v_add_f32_e32 v135, v135, v136
	v_mul_f32_e32 v136, v125, v125
	v_fmac_f32_e32 v136, v124, v124
	v_add_f32_e32 v135, v136, v135
	v_mul_f32_e32 v136, v115, v115
	v_mul_f32_e32 v137, v117, v117
	v_and_b32_e32 v132, 64, v162
	v_fmac_f32_e32 v136, v114, v114
	v_fmac_f32_e32 v137, v116, v116
	v_xor_b32_e32 v133, 16, v162
	v_add_u32_e32 v132, 64, v132
	v_add_f32_e32 v136, v136, v137
	v_mul_f32_e32 v137, v107, v107
	v_cmp_lt_i32_e32 vcc, v133, v132
	v_fmac_f32_e32 v137, v106, v106
	v_add_f32_e32 v136, v136, v137
	v_cndmask_b32_e32 v133, v162, v133, vcc
	v_mul_f32_e32 v137, v109, v109
	v_lshlrev_b32_e32 v134, 2, v133
	v_fmac_f32_e32 v137, v108, v108
	v_add_f32_e32 v136, v137, v136
	ds_bpermute_b32 v137, v134, v135
	v_xor_b32_e32 v133, 32, v162
	v_cmp_lt_i32_e32 vcc, v133, v132
	v_mul_f32_e32 v138, v121, v121
	v_fmac_f32_e32 v138, v120, v120
	v_cndmask_b32_e32 v133, v162, v133, vcc
	v_lshlrev_b32_e32 v133, 2, v133
	s_waitcnt lgkmcnt(0)
	v_add_f32_e32 v135, v135, v137
	ds_bpermute_b32 v137, v133, v135
	v_mul_f32_e32 v139, v101, v101
	v_fmac_f32_e32 v139, v100, v100
	v_mul_f32_e32 v142, v89, v89
	v_fmac_f32_e32 v142, v88, v88
	s_waitcnt lgkmcnt(0)
	v_add_f32_e32 v135, v135, v137
	ds_bpermute_b32 v137, v134, v136
	v_mul_f32_e32 v143, v73, v73
	v_fmac_f32_e32 v143, v72, v72
	s_waitcnt lgkmcnt(0)
	v_add_f32_e32 v136, v136, v137
	ds_bpermute_b32 v137, v133, v136
	s_waitcnt lgkmcnt(0)
;     __device__ __forceinline__ void operator()(const f32x4 (&acc)[2][2][4][2], const Unit& u, int wr, int wc, int fr, int fq) const {
;     ...
;                     const f32x4 a0 = acc[ai][0][m][0], a1 = acc[ai][0][m][1], b0 = acc[ai][1][m][0], b1 = acc[ai][1][m][1];
;                     float s0 = (a0[0] * a0[0] + a0[1] * a0[1]) + (a0[2] * a0[2] + a0[3] * a0[3]) + (a1[0] * a1[0] + a1[1] * a1[1]) + (a1[2] * a1[2] + a1[3] * a1[3]);
;                     float s1 = (b0[0] * b0[0] + b0[1] * b0[1]) + (b0[2] * b0[2] + b0[3] * b0[3]) + (b1[0] * b1[0] + b1[1] * b1[1]) + (b1[2] * b1[2] + b1[3] * b1[3]);
;                     s0 += __shfl_xor(s0, 16); s0 += __shfl_xor(s0, 32); s1 += __shfl_xor(s1, 16); s1 += __shfl_xor(s1, 32);
;                     mx0 = __builtin_fmaxf(mx0, s0); mx1 = __builtin_fmaxf(mx1, s1);
	v_add_f32_e32 v136, v136, v137
	v_mul_f32_e32 v137, v119, v119
	v_fmac_f32_e32 v137, v118, v118
	v_add_f32_e32 v137, v137, v138
	v_mul_f32_e32 v138, v111, v111
	v_fmac_f32_e32 v138, v110, v110
	v_add_f32_e32 v137, v137, v138
	v_mul_f32_e32 v138, v113, v113
	v_fmac_f32_e32 v138, v112, v112
	v_add_f32_e32 v137, v138, v137
	v_mul_f32_e32 v138, v99, v99
	v_fmac_f32_e32 v138, v98, v98
	v_add_f32_e32 v138, v138, v139
	v_mul_f32_e32 v139, v91, v91
	v_fmac_f32_e32 v139, v90, v90
	v_add_f32_e32 v138, v138, v139
	v_mul_f32_e32 v139, v93, v93
	v_fmac_f32_e32 v139, v92, v92
	v_add_f32_e32 v138, v139, v138
	ds_bpermute_b32 v139, v134, v137
	s_waitcnt lgkmcnt(0)
	v_add_f32_e32 v137, v137, v139
	ds_bpermute_b32 v139, v133, v137
	s_waitcnt lgkmcnt(0)
	v_add_f32_e32 v137, v137, v139
	ds_bpermute_b32 v139, v134, v138
	v_max3_f32 v135, v135, 0, v137
	v_mul_f32_e32 v137, v103, v103
	v_fmac_f32_e32 v137, v102, v102
	s_waitcnt lgkmcnt(0)
	v_add_f32_e32 v138, v138, v139
	ds_bpermute_b32 v139, v133, v138
	s_waitcnt lgkmcnt(0)
	v_add_f32_e32 v138, v138, v139
	v_max3_f32 v136, v136, 0, v138
	v_mul_f32_e32 v138, v105, v105
	v_fmac_f32_e32 v138, v104, v104
	v_add_f32_e32 v137, v137, v138
	v_mul_f32_e32 v138, v95, v95
	v_fmac_f32_e32 v138, v94, v94
	v_add_f32_e32 v137, v137, v138
	v_mul_f32_e32 v138, v97, v97
	v_fmac_f32_e32 v138, v96, v96
	v_add_f32_e32 v137, v138, v137
	v_mul_f32_e32 v138, v83, v83
	v_mul_f32_e32 v139, v85, v85
	v_fmac_f32_e32 v138, v82, v82
	v_fmac_f32_e32 v139, v84, v84
	v_add_f32_e32 v138, v138, v139
	v_mul_f32_e32 v139, v75, v75
	v_fmac_f32_e32 v139, v74, v74
	v_add_f32_e32 v138, v138, v139
	v_mul_f32_e32 v139, v77, v77
	v_fmac_f32_e32 v139, v76, v76
	v_add_f32_e32 v138, v139, v138
	ds_bpermute_b32 v139, v134, v137
	s_waitcnt lgkmcnt(0)
	v_add_f32_e32 v137, v137, v139
	ds_bpermute_b32 v139, v133, v137
	s_waitcnt lgkmcnt(0)
	v_add_f32_e32 v137, v137, v139
	ds_bpermute_b32 v139, v134, v138
	s_waitcnt lgkmcnt(0)
	v_add_f32_e32 v138, v138, v139
	ds_bpermute_b32 v139, v133, v138
	s_waitcnt lgkmcnt(0)
	v_add_f32_e32 v138, v138, v139
	v_mul_f32_e32 v139, v87, v87
	v_fmac_f32_e32 v139, v86, v86
	v_add_f32_e32 v139, v139, v142
	v_mul_f32_e32 v142, v79, v79
	v_fmac_f32_e32 v142, v78, v78
	v_add_f32_e32 v139, v139, v142
	v_mul_f32_e32 v142, v81, v81
	v_fmac_f32_e32 v142, v80, v80
	v_add_f32_e32 v139, v142, v139
	v_mul_f32_e32 v142, v71, v71
	v_fmac_f32_e32 v142, v70, v70
	v_add_f32_e32 v142, v142, v143
	v_mul_f32_e32 v143, v67, v67
	v_fmac_f32_e32 v143, v66, v66
	v_add_f32_e32 v142, v142, v143
	v_mul_f32_e32 v143, v69, v69
	v_fmac_f32_e32 v143, v68, v68
	v_add_f32_e32 v142, v143, v142
	ds_bpermute_b32 v143, v134, v139
	s_waitcnt lgkmcnt(0)
	v_add_f32_e32 v139, v139, v143
	ds_bpermute_b32 v143, v133, v139
	s_waitcnt lgkmcnt(0)
	v_add_f32_e32 v139, v139, v143
	ds_bpermute_b32 v143, v134, v142
	v_max3_f32 v135, v135, v137, v139
	v_mul_f32_e32 v137, v63, v63
	v_fmac_f32_e32 v137, v62, v62
	v_mul_f32_e32 v139, v53, v53
	s_waitcnt lgkmcnt(0)
	v_add_f32_e32 v142, v142, v143
	ds_bpermute_b32 v143, v133, v142
	v_fmac_f32_e32 v139, v52, v52
	s_waitcnt lgkmcnt(0)
	v_add_f32_e32 v142, v142, v143
	v_max3_f32 v136, v136, v138, v142
	v_mul_f32_e32 v138, v65, v65
	v_fmac_f32_e32 v138, v64, v64
	v_add_f32_e32 v137, v137, v138
	v_mul_f32_e32 v138, v59, v59
	v_fmac_f32_e32 v138, v58, v58
	v_add_f32_e32 v137, v137, v138
	v_mul_f32_e32 v138, v61, v61
	v_fmac_f32_e32 v138, v60, v60
	v_add_f32_e32 v137, v138, v137
	v_mul_f32_e32 v138, v51, v51
	v_fmac_f32_e32 v138, v50, v50
	v_add_f32_e32 v138, v138, v139
	v_mul_f32_e32 v139, v43, v43
	v_fmac_f32_e32 v139, v42, v42
	v_add_f32_e32 v138, v138, v139
	v_mul_f32_e32 v139, v45, v45
	v_fmac_f32_e32 v139, v44, v44
	v_add_f32_e32 v138, v139, v138
	ds_bpermute_b32 v139, v134, v137
	v_mul_f32_e32 v142, v57, v57
	v_fmac_f32_e32 v142, v56, v56
	v_mul_f32_e32 v143, v37, v37
	v_fmac_f32_e32 v143, v36, v36
	s_waitcnt lgkmcnt(0)
	v_add_f32_e32 v137, v137, v139
	ds_bpermute_b32 v139, v133, v137
	s_waitcnt lgkmcnt(0)
	v_add_f32_e32 v137, v137, v139
	ds_bpermute_b32 v139, v134, v138
	s_waitcnt lgkmcnt(0)
	v_add_f32_e32 v138, v138, v139
	ds_bpermute_b32 v139, v133, v138
	s_waitcnt lgkmcnt(0)
;     __device__ __forceinline__ void operator()(const f32x4 (&acc)[2][2][4][2], const Unit& u, int wr, int wc, int fr, int fq) const {
;     ...
;                     const f32x4 a0 = acc[ai][0][m][0], a1 = acc[ai][0][m][1], b0 = acc[ai][1][m][0], b1 = acc[ai][1][m][1];
;                     float s0 = (a0[0] * a0[0] + a0[1] * a0[1]) + (a0[2] * a0[2] + a0[3] * a0[3]) + (a1[0] * a1[0] + a1[1] * a1[1]) + (a1[2] * a1[2] + a1[3] * a1[3]);
;                     float s1 = (b0[0] * b0[0] + b0[1] * b0[1]) + (b0[2] * b0[2] + b0[3] * b0[3]) + (b1[0] * b1[0] + b1[1] * b1[1]) + (b1[2] * b1[2] + b1[3] * b1[3]);
;                     s0 += __shfl_xor(s0, 16); s0 += __shfl_xor(s0, 32); s1 += __shfl_xor(s1, 16); s1 += __shfl_xor(s1, 32);
;                     mx0 = __builtin_fmaxf(mx0, s0); mx1 = __builtin_fmaxf(mx1, s1);
;                 }
; #pragma unroll
;             for (int o = 1; o < 16; o <<= 1) { mx0 = __builtin_fmaxf(mx0, __shfl_xor(mx0, o)); mx1 = __builtin_fmaxf(mx1, __shfl_xor(mx1, o)); }
;             if ((fr | fq) == 0) { const int bb = u.pm >> 5, pr = (u.pn - 4) * 4 + (wc >> 1), hf = wc & 1;
;                 atomicMax(kb + ((bb * 16 + pr) * 2 + hf), __float_as_uint(mx0)); atomicMax(kb + ((bb * 16 + pr + 2) * 2 + hf), __float_as_uint(mx1)); }
	v_add_f32_e32 v138, v138, v139
	v_mul_f32_e32 v139, v55, v55
	v_fmac_f32_e32 v139, v54, v54
	v_add_f32_e32 v139, v139, v142
	v_mul_f32_e32 v142, v47, v47
	v_fmac_f32_e32 v142, v46, v46
	v_add_f32_e32 v139, v139, v142
	v_mul_f32_e32 v142, v49, v49
	v_fmac_f32_e32 v142, v48, v48
	v_add_f32_e32 v139, v142, v139
	v_mul_f32_e32 v142, v35, v35
	v_fmac_f32_e32 v142, v34, v34
	v_add_f32_e32 v142, v142, v143
	v_mul_f32_e32 v143, v27, v27
	v_fmac_f32_e32 v143, v26, v26
	v_add_f32_e32 v142, v142, v143
	v_mul_f32_e32 v143, v29, v29
	v_fmac_f32_e32 v143, v28, v28
	v_add_f32_e32 v142, v143, v142
	ds_bpermute_b32 v143, v134, v139
	s_waitcnt lgkmcnt(0)
	v_add_f32_e32 v139, v139, v143
	ds_bpermute_b32 v143, v133, v139
	s_waitcnt lgkmcnt(0)
	v_add_f32_e32 v139, v139, v143
	ds_bpermute_b32 v143, v134, v142
	v_max3_f32 v135, v135, v137, v139
	v_mul_f32_e32 v137, v39, v39
	v_fmac_f32_e32 v137, v38, v38
	v_mul_f32_e32 v139, v21, v21
	s_waitcnt lgkmcnt(0)
	v_add_f32_e32 v142, v142, v143
	ds_bpermute_b32 v143, v133, v142
	v_fmac_f32_e32 v139, v20, v20
	s_waitcnt lgkmcnt(0)
	v_add_f32_e32 v142, v142, v143
	v_max3_f32 v136, v136, v138, v142
	v_mul_f32_e32 v138, v41, v41
	v_fmac_f32_e32 v138, v40, v40
	v_add_f32_e32 v137, v137, v138
	v_mul_f32_e32 v138, v31, v31
	v_fmac_f32_e32 v138, v30, v30
	v_add_f32_e32 v137, v137, v138
	v_mul_f32_e32 v138, v33, v33
	v_fmac_f32_e32 v138, v32, v32
	v_add_f32_e32 v137, v138, v137
	v_mul_f32_e32 v138, v19, v19
	v_fmac_f32_e32 v138, v18, v18
	v_add_f32_e32 v138, v138, v139
	v_mul_f32_e32 v139, v11, v11
	v_fmac_f32_e32 v139, v10, v10
	v_add_f32_e32 v138, v138, v139
	v_mul_f32_e32 v139, v13, v13
	v_fmac_f32_e32 v139, v12, v12
	v_add_f32_e32 v138, v139, v138
	ds_bpermute_b32 v139, v134, v137
	v_mul_f32_e32 v142, v25, v25
	v_fmac_f32_e32 v142, v24, v24
	v_mul_f32_e32 v143, v9, v9
	v_fmac_f32_e32 v143, v8, v8
	s_waitcnt lgkmcnt(0)
	v_add_f32_e32 v137, v137, v139
	ds_bpermute_b32 v139, v133, v137
	s_waitcnt lgkmcnt(0)
	v_add_f32_e32 v137, v137, v139
	ds_bpermute_b32 v139, v134, v138
	s_waitcnt lgkmcnt(0)
	v_add_f32_e32 v138, v138, v139
	ds_bpermute_b32 v139, v133, v138
	s_waitcnt lgkmcnt(0)
	v_add_f32_e32 v138, v138, v139
	v_mul_f32_e32 v139, v23, v23
	v_fmac_f32_e32 v139, v22, v22
	v_add_f32_e32 v139, v139, v142
	v_mul_f32_e32 v142, v15, v15
	v_fmac_f32_e32 v142, v14, v14
	v_add_f32_e32 v139, v139, v142
	v_mul_f32_e32 v142, v17, v17
	v_fmac_f32_e32 v142, v16, v16
	v_add_f32_e32 v139, v142, v139
	v_mul_f32_e32 v142, v7, v7
	v_fmac_f32_e32 v142, v6, v6
	v_add_f32_e32 v142, v142, v143
	v_mul_f32_e32 v143, v3, v3
	v_fmac_f32_e32 v143, v2, v2
	v_add_f32_e32 v142, v142, v143
	v_mul_f32_e32 v143, v5, v5
	v_fmac_f32_e32 v143, v4, v4
	v_add_f32_e32 v142, v143, v142
	ds_bpermute_b32 v143, v134, v139
	ds_bpermute_b32 v134, v134, v142
	s_waitcnt lgkmcnt(1)
	v_add_f32_e32 v139, v139, v143
	ds_bpermute_b32 v143, v133, v139
	s_waitcnt lgkmcnt(1)
	v_add_f32_e32 v134, v142, v134
	ds_bpermute_b32 v133, v133, v134
	s_waitcnt lgkmcnt(1)
	v_add_f32_e32 v139, v139, v143
	s_waitcnt lgkmcnt(0)
	v_add_f32_e32 v133, v134, v133
	v_max3_f32 v134, v135, v137, v139
	v_xor_b32_e32 v135, 1, v162
	v_cmp_lt_i32_e32 vcc, v135, v132
	v_max3_f32 v133, v136, v138, v133
	s_nop 0
	v_cndmask_b32_e32 v135, v162, v135, vcc
	v_lshlrev_b32_e32 v135, 2, v135
	ds_bpermute_b32 v136, v135, v134
	ds_bpermute_b32 v135, v135, v133
	s_waitcnt lgkmcnt(1)
	v_max_f32_e32 v136, v136, v136
	s_waitcnt lgkmcnt(0)
	v_max_f32_e32 v135, v135, v135
	v_max_f32_e32 v133, v133, v135
	v_xor_b32_e32 v135, 2, v162
	v_cmp_lt_i32_e32 vcc, v135, v132
	v_max_f32_e32 v134, v134, v136
	s_nop 0
	v_cndmask_b32_e32 v135, v162, v135, vcc
	v_lshlrev_b32_e32 v135, 2, v135
	ds_bpermute_b32 v136, v135, v134
	ds_bpermute_b32 v135, v135, v133
	s_waitcnt lgkmcnt(1)
	v_max_f32_e32 v136, v136, v136
	s_waitcnt lgkmcnt(0)
	v_max_f32_e32 v135, v135, v135
	v_max_f32_e32 v133, v133, v135
	v_xor_b32_e32 v135, 4, v162
	v_cmp_lt_i32_e32 vcc, v135, v132
	v_max_f32_e32 v134, v134, v136
	s_nop 0
	v_cndmask_b32_e32 v135, v162, v135, vcc
	v_lshlrev_b32_e32 v135, 2, v135
	ds_bpermute_b32 v136, v135, v134
	ds_bpermute_b32 v135, v135, v133
	s_waitcnt lgkmcnt(1)
	v_max_f32_e32 v136, v136, v136
	s_waitcnt lgkmcnt(0)
	v_max_f32_e32 v135, v135, v135
	v_max_f32_e32 v133, v133, v135
	v_xor_b32_e32 v135, 8, v162
	v_cmp_lt_i32_e32 vcc, v135, v132
	v_max_f32_e32 v134, v134, v136
	s_nop 0
	v_cndmask_b32_e32 v132, v162, v135, vcc
	v_lshlrev_b32_e32 v132, 2, v132
	ds_bpermute_b32 v135, v132, v134
	ds_bpermute_b32 v132, v132, v133
	s_and_saveexec_b64 s[10:11], s[4:5]
	s_cbranch_execz .LBB0_130
	s_waitcnt lgkmcnt(1)
	v_max_f32_e32 v135, v135, v135
	v_max_f32_e32 v134, v134, v134
	s_mov_b64 s[22:23], exec
	v_max_f32_e32 v134, v134, v135
	s_mov_b32 s13, 0

; #define PG8_BAR __builtin_amdgcn_s_barrier()
; template <class Epi, class Sched, bool ALIGN_EPI = false, bool SP2 = false>
; __device__ __forceinline__ void gemm_phase(LAS unsigned char* lds, const Gemm g, const Sched& S, const Epi& E) {
;     ...
;         cur = nxt; cA = nA; cB = nB; ++ui;
;         if constexpr (ALIGN_EPI) { if (wr == 1) PG8_BAR; }
.Lkv_after:
	s_andn2_b64 vcc, exec, s[18:19]
	s_cbranch_vccnz .LBB0_108
	s_branch .LBB0_108

; #define PG8_WAIT_V(n) asm volatile("s_waitcnt vmcnt(" #n ")" ::: "memory")
; #define PG8_BAR __builtin_amdgcn_s_barrier()
; template <class Epi, class Sched, bool ALIGN_EPI = false, bool SP2 = false>
; __device__ __forceinline__ void gemm_phase(LAS unsigned char* lds, const Gemm g, const Sched& S, const Epi& E) {
;     ...
;     PG8_WAIT_V(0);
;     if constexpr (!ALIGN_EPI) { if (wr == 0) PG8_BAR; }
;     PG8_BAR;
.LBB0_138:
	s_waitcnt vmcnt(0)
	s_and_b64 vcc, exec, s[90:91]
	s_cbranch_vccz .Lgemm_na_skip
	s_barrier
.Lgemm_na_skip:
	v_readlane_b32 s30, v233, 37
	v_readlane_b32 s56, v232, 13
	v_readlane_b32 s58, v232, 15
	v_readlane_b32 s60, v232, 17
	v_readlane_b32 s62, v232, 19
	v_readlane_b32 s64, v232, 21
	v_readlane_b32 s66, v232, 23
	v_readlane_b32 s68, v232, 25
	v_readlane_b32 s70, v232, 27
	v_readlane_b32 s72, v232, 29
	v_readlane_b32 s74, v232, 31
	v_readlane_b32 s76, v232, 33
	v_readlane_b32 s78, v232, 35
	v_readlane_b32 s82, v232, 37
	v_readlane_b32 s88, v232, 39
	v_readlane_b32 s90, v232, 41
	v_readlane_b32 s94, v232, 43
	v_readlane_b32 s20, v232, 45
	v_readlane_b32 s38, v232, 10
	v_readlane_b32 s31, v233, 38
	v_readlane_b32 s26, v232, 12
	v_readlane_b32 s57, v232, 14
	v_readlane_b32 s59, v232, 16
	v_readlane_b32 s61, v232, 18
	v_readlane_b32 s63, v232, 20
	v_readlane_b32 s65, v232, 22
	v_readlane_b32 s67, v232, 24
	v_readlane_b32 s69, v232, 26
	v_readlane_b32 s71, v232, 28
	v_readlane_b32 s73, v232, 30
	v_readlane_b32 s75, v232, 32
	v_readlane_b32 s77, v232, 34
	v_readlane_b32 s79, v232, 36
	v_readlane_b32 s83, v232, 38
	v_readlane_b32 s89, v232, 40
	v_readlane_b32 s91, v232, 42
	v_readlane_b32 s95, v232, 44
	v_readlane_b32 s21, v232, 46
	v_readlane_b32 s29, v232, 47
	s_barrier
	v_readlane_b32 s39, v232, 11
